# static heavy/light pairing of FoX and MLA q-tiles across the two workgroup slots of a CU; S5/NSA tasks stay dynamic
# speedup vs baseline: 1.0218x; 1.0046x over previous
; DI int otid() { int z; asm volatile("s_mov_b32 %0, 0" : "=s"(z)); return (int)threadIdx.x + z; }
; #define LAS __attribute__((address_space(3)))
; __device__ __forceinline__ unsigned xb_xcc_id() { return (unsigned)__builtin_amdgcn_s_getreg((3 << 11) | 20) & 0xFu; }
; __global__ void __launch_bounds__(256, LB2) mega(Params p, int ph_lo, int ph_hi) {
;   __shared__ __attribute__((aligned(16))) char smem[SM_TOTAL];
;   __shared__ int s_task;
;   __shared__ uint4 xb_words;
;   if (threadIdx.x == 0) xb_words = make_uint4(0u, 0u, 0u, 0u);
;   __syncthreads();
;   (void)xcd_barrier_post((unsigned*)(p.ws + WS_BAR), (volatile LAS unsigned*)&xb_words);
;   const int bid = blockIdx.x, nb = gridDim.x;
;   for (int ph = ph_lo; ph <= ph_hi; ++ph) {
;     if (ph > ph_lo) {
;       if (ph_hi > (1 << 20)) cg::this_grid().sync();
;       else {
;         XcdBarrier xb2;
;         xb2.bar = (unsigned*)(((const Params*)__builtin_amdgcn_kernarg_segment_ptr())->ws + WS_BAR);
;         xb2.x = xb_xcc_id();
;         xb2.st = (volatile LAS unsigned*)&xb_words;
;         xcd_barrier(xb2);
;       }
;     }
;     const int nrep = (REP_PH >= 0 && ph == REP_PH) ? 2 : 1;
;     for (int rep = 0; rep < nrep; ++rep) {
;     if (rep) cg::this_grid().sync();
;     const int tid = otid(), lane = tid & 63, w = tid >> 6, r = lane & 31, h = lane >> 5;
;     const int vb = (bid & 7) * (nb >> 3) + (bid >> 3);
;     int zoff_;
;     asm volatile("s_mov_b32 %0, 0" : "=s"(zoff_));
;     const Params& p = *(const Params*)((const char*)__builtin_amdgcn_kernarg_segment_ptr() + zoff_);
;     char* ws = p.ws;
;     char* const ws_ph = ws;
;     bf16* XN = (bf16*)(ws + WS_XN);
;     bf16* P = (bf16*)(ws + WS_P);
;     bf16* MIXED = (bf16*)(ws + WS_MIXED);
;     float* ROPEC = (float*)(ws + WS_ROPEC);
;     float* ROPES = (float*)(ws + WS_ROPES);
;     float* hbuf = p.out;
;     int* CTR = (int*)(ws + WS_CTR);
.LBB0_6:
	v_readlane_b32 s8, v254, 1
	v_readlane_b32 s9, v254, 2
	s_load_dword s94, s[8:9], 0xf8
	v_readlane_b32 s7, v254, 0
	s_and_b32 s12, s7, 7
	s_ashr_i32 s4, s7, 3
	s_movk_i32 s63, 0x400
	s_waitcnt lgkmcnt(0)
	s_ashr_i32 s2, s94, 3
	s_mul_i32 s0, s2, s12
	s_add_i32 s13, s0, s4
	s_and_b32 s3, s94, 7
	s_cmp_eq_u32 s3, 0
	s_cselect_b64 s[0:1], -1, 0
	s_and_b64 s[0:1], s[0:1], exec
	s_cselect_b32 s5, s4, s7
	s_cselect_b32 s0, s4, s13
	s_lshl_b32 s6, s12, 10
	s_cmp_eq_u32 s3, 0
	s_cselect_b64 s[14:15], -1, 0
	v_writelane_b32 v254, s0, 5
	s_and_b64 s[0:1], s[14:15], exec
	s_cselect_b32 s51, s63, 0x2000
	s_cselect_b32 s1, s2, s94
	s_cselect_b32 s6, s6, 0
	s_add_u32 s2, s8, 0xf8
	s_addc_u32 s3, s9, 0
	v_writelane_b32 v254, s2, 6
	s_cmp_lt_i32 s11, 0x100001
	v_lshrrev_b32_e32 v1, 20, v0
	v_lshrrev_b32_e32 v0, 10, v0
	v_writelane_b32 v254, s3, 7
	s_cselect_b64 s[2:3], -1, 0
	v_or_b32_e32 v0, v0, v1
	s_movk_i32 s0, 0x3ff
	v_writelane_b32 v254, s2, 8
	v_and_or_b32 v0, v0, s0, v189
	s_cmp_eq_u32 s7, 0
	v_writelane_b32 v254, s3, 9
	v_cmp_eq_u32_e64 s[2:3], 0, v0
	s_mov_b32 s82, s10
	s_movk_i32 s80, 0xff00
	v_writelane_b32 v254, s2, 10
	v_mbcnt_lo_u32_b32 v0, -1, 0
	s_mov_b32 s65, 0
	s_mov_b32 s81, -1
	v_writelane_b32 v255, s81, 60
	v_writelane_b32 v254, s3, 11
	s_cselect_b64 s[2:3], -1, 0
	v_writelane_b32 v254, s2, 12
	s_lshl_b32 s0, s7, 8
	s_lshl_b32 s8, s94, 8
	v_writelane_b32 v254, s3, 13
	v_writelane_b32 v254, s0, 14
	s_lshl_b32 s0, s7, 2
	v_writelane_b32 v254, s0, 15
	s_lshl_b32 s0, s5, 2
	v_writelane_b32 v254, s0, 16
	v_writelane_b32 v254, s1, 17
	s_lshl_b32 s0, s1, 3
	s_lshl_b32 s52, s94, 2
	s_lshl_b32 s16, s1, 2
	v_writelane_b32 v254, s0, 18
	s_lshl_b32 s0, s12, 1
	s_cmpk_lt_i32 s7, 0x540
	v_writelane_b32 v254, s0, 19
	s_cselect_b64 s[0:1], -1, 0
	v_writelane_b32 v254, s0, 20
	s_cmpk_lt_i32 s13, 0x200
	s_movk_i32 s95, 0x2000
	v_writelane_b32 v254, s1, 21
	s_cselect_b64 s[0:1], -1, 0
	v_writelane_b32 v254, s0, 22
	s_cmp_gt_i32 s94, 63
	v_add_u32_e32 v208, 0x100, v189
	v_writelane_b32 v254, s1, 23
	s_cselect_b64 s[0:1], -1, 0
	s_sub_i32 s2, s94, 32
	s_lshr_b32 s5, s2, 3
	s_mul_i32 s5, s5, s12
	s_add_i32 s4, s4, s5
	v_writelane_b32 v254, s14, 24
	s_and_b64 s[0:1], s[0:1], s[14:15]
	s_add_i32 s4, s4, 28
	s_cmp_gt_i32 s7, 15
	v_writelane_b32 v254, s15, 25
	s_cselect_b64 s[14:15], -1, 0
	s_cmp_lt_i32 s7, 32
	s_cselect_b32 s2, 0x10000000, s2
	s_cselect_b32 s4, s7, s4
	s_and_b64 s[0:1], s[0:1], exec
	v_writelane_b32 v254, s12, 26
	s_cselect_b32 s4, s4, s7
	v_writelane_b32 v254, s14, 27
	s_cselect_b32 s84, s2, s94
	s_cmpk_gt_i32 s4, 0x81f
	v_writelane_b32 v254, s15, 28
	s_cselect_b64 s[0:1], -1, 0
	v_writelane_b32 v254, s0, 29
	s_movk_i32 s3, 0x200
	v_add_u32_e32 v209, 0x200, v189
	v_writelane_b32 v254, s1, 30
	s_abs_i32 s0, s94
	s_sub_i32 s1, 1, s0
	s_cmp_lt_u32 s0, 2
	s_cselect_b32 s1, s1, 1
	s_sub_i32 s2, s1, s0
	s_cmp_ge_u32 s1, s0
	s_cselect_b32 s0, s2, s1
	s_cmp_eq_u32 s7, s0
	s_cselect_b64 s[0:1], -1, 0
	v_writelane_b32 v254, s0, 31
	s_ashr_i32 s9, s8, 31
	s_ashr_i32 s53, s52, 31
	v_writelane_b32 v254, s1, 32
	s_mov_b32 s0, s8
	v_writelane_b32 v254, s0, 33
	s_lshl_b64 s[54:55], s[52:53], 12
	s_lshl_b64 s[36:37], s[52:53], 13
	v_writelane_b32 v254, s1, 34
	s_lshl_b64 s[0:1], s[8:9], 2
	v_writelane_b32 v254, s0, 35
	s_lshl_b32 s85, s94, 4
	s_lshl_b32 s61, s84, 7
	v_writelane_b32 v254, s1, 36
	v_writelane_b32 v254, s6, 37
	v_writelane_b32 v254, s16, 38
	s_add_i32 s0, s6, s16
	v_writelane_b32 v254, s0, 39
	s_lshl_b32 s0, s13, 4
	v_writelane_b32 v254, s0, 40
	s_lshl_b32 s0, s4, 7
	v_writelane_b32 v254, s0, 41
	v_writelane_b32 v254, s4, 42
	s_lshl_b32 s0, s4, 6
	v_writelane_b32 v254, s0, 43
	s_lshl_b32 s0, s84, 6
	s_bitcmp1_b32 s7, 0
	v_writelane_b32 v254, s0, 44
	s_cselect_b64 s[0:1], -1, 0
	v_writelane_b32 v254, s0, 45
	v_add_u32_e32 v210, 0x300, v189
	v_or_b32_e32 v211, 0x400, v189
	v_writelane_b32 v254, s1, 46
	v_writelane_b32 v254, s13, 47
	s_lshl_b32 s0, s13, 5
	v_writelane_b32 v254, s0, 48
	s_lshl_b32 s0, s94, 5
	v_writelane_b32 v254, s0, 49
	v_writelane_b32 v254, s94, 50
	s_mov_b32 s0, s52
	v_writelane_b32 v254, s0, 51
	v_add_u32_e32 v212, 0x500, v189
	v_mov_b32_e32 v213, 0x12400
	v_writelane_b32 v254, s1, 52
	v_writelane_b32 v254, s84, 53
	v_writelane_b32 v254, s36, 54
	v_mov_b32_e32 v214, 0x12404
	v_mov_b32_e32 v1, 0
	v_writelane_b32 v254, s37, 55
	v_writelane_b32 v254, s85, 56
	v_writelane_b32 v254, s61, 57
	v_writelane_b32 v254, s10, 58
	s_mov_b32 s58, 0x2aaaaaab
	s_mov_b32 s59, 0x7f800000
	v_writelane_b32 v254, s11, 59
	v_writelane_b32 v254, s51, 60
	v_writelane_b32 v254, s54, 61
	s_mov_b32 s66, 0x3fb8aa3b
	s_mov_b32 s72, 0x800000
	v_mov_b32_e32 v217, 0x3c0881c4
	v_mov_b32_e32 v218, 0xbab64f3b
	v_mov_b32_e32 v187, 1.0
	s_movk_i32 s74, 0x1400
	v_mov_b32_e32 v188, 0x358637bd
	s_movk_i32 s75, 0x1080
	s_movk_i32 s42, 0x90
	s_movk_i32 s57, 0x210
	s_movk_i32 s78, 0x1ff
	s_movk_i32 s70, 0x3900
	s_movk_i32 s71, 0x2ff
	s_movk_i32 s67, 0x3500
	v_mov_b32_e32 v219, 0x12410
	s_movk_i32 s43, 0x800
	v_mov_b32_e32 v229, 0x3ecc95a3
	s_movk_i32 s73, 0x110
	s_movk_i32 s68, 0x88
	s_mov_b32 s69, 0x3e0293ee
	s_movk_i32 s2, 0x880
	s_movk_i32 s88, 0x320
	s_movk_i32 s89, 0x31f
	s_mov_b32 s76, 0x51eb851f
	s_mov_b32 s77, 0x3f317217
	s_mov_b32 s79, 0x40851592
	s_brev_b32 s92, -4
	s_movk_i32 s93, 0x31e
	s_mov_b32 s81, -1
	s_movk_i32 s33, 0x190
	v_mov_b32_e32 v215, 0x461c4000
	v_mov_b32_e32 v216, 0x37000000
	v_mov_b32_e32 v224, 0x7f800000
	v_not_b32_e32 v225, 63
	v_not_b32_e32 v226, 31
	v_mov_b32_e32 v227, 0x7fc00000
	v_mbcnt_hi_u32_b32 v228, -1, v0
	v_mov_b32_e32 v190, 0x3f317218
	v_mov_b32_e32 v230, 0xf149f2ca
	v_mov_b32_e32 v231, 0x12000
	v_mov_b32_e32 v232, 0x3fe
	v_mov_b32_e32 v233, 0xa900
	v_mov_b32_e32 v234, 0x41b17218
	v_mov_b32_e32 v235, 0xdb00
	v_mov_b32_e32 v236, 0x31f
	v_mov_b32_e32 v237, 0x11d00
	v_writelane_b32 v254, s55, 62
	s_branch .LBB0_8

; __global__ void __launch_bounds__(256, LB2) mega(Params p, int ph_lo, int ph_hi) {
;     ...
;     if ((PHM & 16) && sub == 2 && even) {
;       const int n_fox = 512, n_s5 = 1024;
;       for (int qd_ = 0; qd_ < 8; ++qd_) {
;       const int xq_ = ((bid & 7) + qd_) & 7;
;       for (;;) {
;         const int i_ = fetch_task(CTR + 64 + ph * 8 + xq_);
;         if (i_ >= 64 + 128) break;
;         const int t = i_ < 64 ? i_ * 8 + xq_ : n_fox + (i_ - 64) * 8 + xq_;
.LBB0_299:
	s_cmp_eq_u32 s56, 2
	s_cselect_b64 s[0:1], -1, 0
	v_readlane_b32 s4, v255, 8
	s_and_b64 s[0:1], s[0:1], s[96:97]
	v_readlane_b32 s5, v255, 9
	s_lshl_b32 s14, s4, 3
	v_writelane_b32 v255, s0, 20
	s_ashr_i32 s15, s14, 31
	s_andn2_b64 vcc, exec, s[0:1]
	v_writelane_b32 v255, s1, 21
	v_cmp_eq_u32_e64 s[6:7], 0, v192
	s_cbranch_vccnz .LBB0_350
	s_ashr_i32 s23, s22, 31
	s_lshl_b64 s[4:5], s[22:23], 16
	s_lshl_b32 s16, s22, 10
	s_lshl_b64 s[0:1], s[14:15], 2
	s_add_u32 s0, s30, s0
	s_addc_u32 s1, s31, s1
	s_add_u32 s36, s0, 0xfed1100
	s_addc_u32 s37, s1, 0
	s_add_u32 s40, s30, 0x5e01800
	s_addc_u32 s41, s31, 0
	s_add_u32 s42, s30, 0xfcc1000
	s_mov_b32 s17, 0
	s_addc_u32 s43, s31, 0
	v_readlane_b32 s44, v254, 0
	v_readlane_b32 s0, v254, 50
	v_readlane_b32 s1, v254, 0
	s_lshr_b32 s1, s1, 3
	s_sub_i32 s8, 0x5f, s1
	s_cmp_lt_u32 s1, 32
	s_cselect_b32 s1, s1, s8
	s_cmpk_eq_u32 s0, 0x200
	s_cselect_b32 s1, s1, -1
	s_cselect_b32 s8, 64, 0
	s_movk_i32 s0, 0xbf
	s_cselect_b32 s0, 0x7f, s0
	v_writelane_b32 v255, s1, 60
	v_writelane_b32 v255, s8, 61
	v_writelane_b32 v255, s0, 62
	s_branch .LBB0_302

; __global__ void __launch_bounds__(256, LB2) mega(Params p, int ph_lo, int ph_hi) {
;     ...
;       for (int qd_ = 0; qd_ < 8; ++qd_) {
;       const int xq_ = ((bid & 7) + qd_) & 7;
;       for (;;) {
;         const int i_ = fetch_task(CTR + 64 + ph * 8 + xq_);
;         if (i_ >= 64 + 128) break;
;         const int t = i_ < 64 ? i_ * 8 + xq_ : n_fox + (i_ - 64) * 8 + xq_;
.LBB0_306:
	v_readlane_b32 s8, v255, 60
	s_cmp_lt_i32 s8, 0
	s_cbranch_scc1 .Lfoxq_fetch
	s_mov_b32 s0, -1
	v_writelane_b32 v255, s0, 60
	s_branch .Lfoxq_go

; DI float bflo(unsigned u) { return __uint_as_float(u << 16); }
; DI float bfhi(unsigned u) { return __uint_as_float(u & 0xffff0000u); }
; __global__ void __launch_bounds__(256, LB2) mega(Params p, int ph_lo, int ph_hi) {
;     ...
;       for (;;) {
;         const int i_ = fetch_task(CTR + 64 + ph * 8 + xq_);
;         if (i_ >= 64 + 128) break;
;         const int t = i_ < 64 ? i_ * 8 + xq_ : n_fox + (i_ - 64) * 8 + xq_;
;     ...
;           const int t2 = t - n_fox;
;           const int ch = t2 >> 4, gq = t2 & 15;
;           float* us = (float*)smem;
;           float* xs = (float*)(smem + 32768) + w * 16 * 132;
;           __syncthreads();
;           for (int i = tid; i < 128 * 8; i += 256) {
;             int tt = i >> 3, c8 = (i & 7) * 8;
;             uint4 u = *(const uint4*)(P + (size_t)(ch * 128 + tt) * NPE + gq * 64 + c8);
;             float* d = us + tt * 64 + c8;
;             d[0] = bflo(u.x); d[1] = bfhi(u.x); d[2] = bflo(u.y); d[3] = bfhi(u.y);
;             d[4] = bflo(u.z); d[5] = bfhi(u.z); d[6] = bflo(u.w); d[7] = bfhi(u.w);
;           }
.LBB0_310:
	s_or_b64 exec, exec, s[0:1]
	s_waitcnt lgkmcnt(0)
	s_barrier
	v_readlane_b32 s0, v255, 62
	ds_read_b32 v0, v219
	s_nop 0
	s_waitcnt lgkmcnt(0)
	v_cmp_lt_i32_e32 vcc, s0, v0
	v_readfirstlane_b32 s8, v0
	s_mov_b64 s[0:1], -1
	s_cbranch_vccnz .LBB0_305
	v_readlane_b32 s24, v255, 61
	s_add_i32 s8, s8, s24
.Lfoxq_go:
	s_lshl_b32 s24, s8, 3
	s_or_b32 s20, s24, s46
	s_mov_b32 s0, 0
	s_mov_b32 s26, 0
	s_ashr_i32 s27, s26, 31
	s_add_u32 s8, s30, s26
	v_add_u32_e32 v44, s0, v189
	s_addc_u32 s9, s31, s27
	v_and_b32_e32 v45, 63, v44
	v_ashrrev_i32_e32 v46, 6, v44
	s_cmpk_gt_i32 s20, 0x1ff
	s_mov_b64 s[0:1], -1
	s_cbranch_scc0 .LBB0_327
	s_add_i32 s34, s24, 0xfffffe00
	s_lshr_b32 s25, s34, 4
	s_and_b32 s35, s20, 15
	v_cmp_gt_i32_e32 vcc, s63, v44
	s_barrier
	s_and_saveexec_b64 s[0:1], vcc
	s_cbranch_execz .LBB0_315
	s_lshl_b32 s51, s25, 7
	s_lshl_b32 s20, s35, 7
	s_add_u32 s20, s90, s20
	s_addc_u32 s21, s91, 0
	v_lshlrev_b32_e32 v2, 3, v44
	s_mov_b64 s[22:23], 0
	v_mov_b32_e32 v3, v44

; __global__ void __launch_bounds__(256, LB2) mega(Params p, int ph_lo, int ph_hi) {
;     ...
;     if ((PHM & 256) && sub == 3 && !even) {
;       const int* pos = p.pos;
;       float* lut = (float*)(smem + AT_X0);
;       float* imp = (float*)(smem + AT_IMP);
;       unsigned* sel = (unsigned*)(smem + AT_SEL);
;       const float* GT = (const float*)(ws + WS_FLOG);
;       float* NSAO = (float*)(ws + WS_NSAO);
;       for (int qd_ = 0; qd_ < 8; ++qd_) {
;       const int xq_ = ((bid & 7) + qd_) & 7;
;       for (;;) {
;         const int i_ = fetch_task(CTR + 64 + ph * 8 + xq_);
;         if (i_ >= 128) break;
;         const int tt_ = 2 * ((i_ >> 1) * 8 + xq_) + (i_ & 1);
;         const int t = tt_ >> 1;
.LBB0_456:
	s_cmp_lg_u32 s56, 3
	s_cselect_b64 s[0:1], -1, 0
	s_or_b64 s[4:5], s[0:1], s[96:97]
	s_and_b64 vcc, exec, s[4:5]
	s_cbranch_vccnz .LBB0_915
	v_writelane_b32 v255, s4, 24
	s_add_u32 s24, s30, 0xfa80000
	s_addc_u32 s25, s31, 0
	v_writelane_b32 v255, s5, 25
	v_readlane_b32 s6, v254, 45
	v_readlane_b32 s0, v255, 4
	v_readlane_b32 s1, v255, 5
	s_load_dwordx2 s[20:21], s[0:1], 0x10
	s_add_u32 s0, s30, 0x14057000
	s_addc_u32 s1, s31, 0
	v_writelane_b32 v255, s0, 6
	s_mov_b32 s5, 0
	v_cmp_eq_u32_e64 s[8:9], 0, v192
	v_writelane_b32 v255, s1, 7
	s_lshl_b64 s[0:1], s[14:15], 2
	s_add_u32 s0, s30, s0
	s_addc_u32 s1, s31, s1
	s_add_u32 s0, s0, 0xfed1100
	v_writelane_b32 v255, s0, 18
	s_addc_u32 s0, s1, 0
	v_writelane_b32 v255, s0, 26
	s_add_u32 s0, s30, 0x5e01c00
	v_writelane_b32 v255, s0, 27
	s_addc_u32 s0, s31, 0
	v_writelane_b32 v255, s0, 28
	s_add_u32 s0, s30, 0x5e02000
	v_writelane_b32 v255, s0, 30
	s_addc_u32 s0, s31, 0
	s_add_u32 s94, s30, 0x5e03400
	s_addc_u32 s95, s31, 0
	v_writelane_b32 v255, s0, 32
	s_add_u32 s0, s30, 0x14017000
	v_writelane_b32 v255, s0, 34
	s_addc_u32 s0, s31, 0
	s_add_u32 s86, s30, 0xfed6004
	v_writelane_b32 v255, s0, 36
	s_addc_u32 s18, s31, 0
	v_readlane_b32 s0, v254, 50
	v_readlane_b32 s10, v254, 0
	s_lshr_b32 s10, s10, 3
	s_sub_i32 s12, 0x5f, s10
	s_cmp_lt_u32 s10, 32
	s_cselect_b32 s10, s10, s12
	s_cmpk_eq_u32 s0, 0x200
	s_cselect_b32 s10, s10, -1
	s_cselect_b32 s12, 1, 0
	s_movk_i32 s0, 0x7f
	s_cselect_b32 s0, 0x3f, s0
	v_writelane_b32 v255, s10, 60
	v_writelane_b32 v255, s12, 61
	v_writelane_b32 v255, s0, 62
	v_readlane_b32 s7, v254, 46
	v_readlane_b32 s0, v254, 0
	s_branch .LBB0_459

; __global__ void __launch_bounds__(256, LB2) mega(Params p, int ph_lo, int ph_hi) {
;     ...
;       for (;;) {
;         const int i_ = fetch_task(CTR + 64 + ph * 8 + xq_);
;         if (i_ >= 128) break;
;         const int tt_ = 2 * ((i_ >> 1) * 8 + xq_) + (i_ & 1);
;         const int t = tt_ >> 1;
.LBB0_463:
	v_readlane_b32 s51, v255, 60
	s_cmp_lt_i32 s51, 0
	s_cbranch_scc1 .Lmlaq_fetch
	s_mov_b64 s[0:1], -1
	v_writelane_b32 v255, s0, 60
	s_lshl_b32 s51, s51, 1
	s_branch .Lmlaq_go

; DI int otid() { int z; asm volatile("s_mov_b32 %0, 0" : "=s"(z)); return (int)threadIdx.x + z; }
; __global__ void __launch_bounds__(256, LB2) mega(Params p, int ph_lo, int ph_hi) {
;     ...
;         const int i_ = fetch_task(CTR + 64 + ph * 8 + xq_);
;         if (i_ >= 128) break;
;         const int tt_ = 2 * ((i_ >> 1) * 8 + xq_) + (i_ & 1);
;         const int t = tt_ >> 1;
;         const int tid = otid(), lane = tid & 63, w = tid >> 6, r = lane & 31, h = lane >> 5;
;         int zt_;
;         asm volatile("s_mov_b32 %0, 0" : "=s"(zt_));
;         char* const ws = ws_ph + zt_;
;         if ((tt_ & 1) == 0) {
;           const int qt = 63 - (t >> 3), head = t & 7;
;           const int q0w = qt * 128 + w * 32, tq = q0w + r;
;           bf16x8 qf[12];
;           load_q<192>(qf, (const bf16*)(ws + WS_QMLA) + (size_t)tq * 1536 + head * 192, h);
;           f32x16 o[4];
;           zero_o(o);
;           float m = NEG, l = 0.f;
;           CtxCausal ctx{tq, q0w, 2 * qt + 1, 0.07216878364870322f * LOG2E};
;           attn_run<192, true, true>(qf, o, m, l, (const bf16*)(ws + WS_KMLA) + head * 128, 1024, P + 6656, NPO,
;                               (const bf16*)(ws + WS_VTMLA) + (size_t)head * 128 * L, L, 0, ctx, smem);
;           float lt = l + __shfl_xor(l, 32);
;           store_out_A(o, 1.f / lt, P + (size_t)tq * NPO + 1024 + head * 128, MIXED + (size_t)tq * MIXW + head * 128, h);
;           continue;
;         }
;         const int qt = 255 - (t >> 1), g = t & 1;
;         const int q0 = qt * 32;
;         const int hr = r >> 3, qi = r & 7;
;         const int ql = w * 8 + qi;
;         const int tq = q0 + ql;
;         const int head = g * 4 + hr;
;         const int posq = pos[tq];
;         __syncthreads();
;         for (int i = tid; i < 4 * 800; i += 256) {
;           int rr = i / 800, n = i % 800;
;           int b;
;           if (n < 16) b = n;
;           else {
;             float lr = logf((float)n / 16.f) / 4.1588830833596715f;
;             b = 16 + (int)(lr * 16.f);
;             if (b > 31) b = 31;
;           }
;           lut[i] = p.t5[b * 8 + g * 4 + rr] * LOG2E;
.LBB0_467:
	s_or_b64 exec, exec, s[0:1]
	s_waitcnt lgkmcnt(0)
	s_barrier
	v_readlane_b32 s6, v255, 62
	ds_read_b32 v0, v219
	s_mov_b64 s[0:1], -1
	s_waitcnt lgkmcnt(0)
	v_cmp_lt_i32_e32 vcc, s6, v0
	v_readfirstlane_b32 s51, v0
	s_cbranch_vccnz .LBB0_462
	v_readlane_b32 s6, v255, 61
	s_lshl_b32 s51, s51, s6
	s_or_b32 s51, s51, s6
.Lmlaq_go:
	s_mov_b32 s26, 0
	s_mov_b32 s64, 0
	s_ashr_i32 s85, s64, 31
	s_add_u32 s48, s30, s64
	s_addc_u32 s49, s31, s85
	s_bitcmp1_b32 s51, 0
	v_add_u32_e32 v2, s26, v189
	s_cselect_b64 s[6:7], -1, 0
	v_ashrrev_i32_e32 v155, 6, v2
	v_and_b32_e32 v157, 31, v2
	v_bfe_u32 v191, v2, 5, 1
	s_and_b64 vcc, exec, s[6:7]
	s_cbranch_vccz .LBB0_850
	s_lshl_b32 s0, s51, 2
	s_and_b32 s0, s0, 0xffffff8
	s_or_b32 s0, s0, s82
	s_lshl_b32 s0, s0, 4
	s_andn2_b32 s0, s0, 31
	v_and_b32_e32 v165, 7, v2
	v_lshlrev_b32_e32 v166, 3, v155
	s_sub_i32 s34, 0x1fe0, s0
	v_or_b32_e32 v147, v166, v165
	v_add_u32_e32 v150, s34, v147
	v_ashrrev_i32_e32 v151, 31, v150
	v_lshl_add_u64 v[4:5], v[150:151], 2, s[20:21]
	global_load_dword v162, v[4:5], off
	s_movk_i32 s0, 0xc80
	v_cmp_gt_i32_e32 vcc, s0, v2
	s_barrier
	s_and_saveexec_b64 s[0:1], vcc
	s_cbranch_execz .LBB0_479
	v_readlane_b32 s6, v255, 4
	v_readlane_b32 s7, v255, 5
	s_load_dwordx2 s[6:7], s[6:7], 0x30
	v_max_i32_e32 v0, 0xb80, v2
	v_sub_u32_e32 v0, v0, v2
	v_add_u32_e32 v0, 0xff, v0
	s_movk_i32 s10, 0xff
	v_cmp_lt_u32_e32 vcc, s10, v0
	s_mov_b64 s[10:11], -1
	v_mov_b32_e32 v3, v2
	s_and_saveexec_b64 s[12:13], vcc
	s_cbranch_execz .LBB0_474
	v_lshrrev_b32_e32 v0, 8, v0
	v_add_u32_e32 v0, 1, v0
	v_and_b32_e32 v6, 0x1fffffe, v0
	v_add_u32_e32 v3, 0x100, v2
	v_lshl_add_u32 v7, v2, 2, v233
	s_mov_b64 s[14:15], 0
	v_mov_b32_e32 v8, v6
	v_mov_b64_e32 v[4:5], v[2:3]
